# no L2 write-back at the barriers after P3 and P4: everything later phases need from those phases (GDN T fragments, M, Bm; GDN chunk states) is stored write-through (sc1) instead
# speedup vs baseline: 1.0067x; 1.0036x over previous
.LBB0_858:
	s_andn2_b64 vcc, exec, s[12:13]
	s_cbranch_vccnz .LBB0_860
	v_and_b32_e32 v0, -16, v82
	v_lshlrev_b32_e32 v1, 2, v23
	v_cmp_lt_u64_e32 vcc, s[24:25], v[182:183]
	v_add3_u32 v12, s93, v0, v1
	s_and_b64 s[12:13], vcc, exec
	ds_read_b128 v[0:3], v12
	ds_read_b128 v[4:7], v12 offset:64
	s_mov_b32 s12, 0x48000
	s_cselect_b32 s12, s12, 0xf348800
	s_add_u32 s12, s10, s12
	s_addc_u32 s13, s11, 0
	s_waitcnt lgkmcnt(1)
	v_cvt_pk_bf16_f32 v0, v0, v1
	v_cvt_pk_bf16_f32 v1, v2, v3
	s_waitcnt lgkmcnt(0)
	v_cvt_pk_bf16_f32 v2, v4, v5
	v_cvt_pk_bf16_f32 v3, v6, v7
	v_lshl_add_u64 v[10:11], v[82:83], 4, s[12:13]
	global_store_dwordx4 v[10:11], v[0:3], off sc1
	ds_read_b128 v[0:3], v12 offset:4352
	ds_read_b128 v[4:7], v12 offset:4416
	s_movk_i32 s12, 0x1000
	s_waitcnt lgkmcnt(1)
	v_cvt_pk_bf16_f32 v0, v0, v1
	v_cvt_pk_bf16_f32 v1, v2, v3
	s_waitcnt lgkmcnt(0)
	v_cvt_pk_bf16_f32 v2, v4, v5
	v_cvt_pk_bf16_f32 v3, v6, v7
	global_store_dwordx4 v[10:11], v[0:3], off offset:1024 sc1
	ds_read_b128 v[0:3], v12 offset:8704
	ds_read_b128 v[4:7], v12 offset:8768
	s_waitcnt lgkmcnt(1)
	v_cvt_pk_bf16_f32 v0, v0, v1
	v_cvt_pk_bf16_f32 v1, v2, v3
	s_waitcnt lgkmcnt(0)
	v_cvt_pk_bf16_f32 v2, v4, v5
	v_cvt_pk_bf16_f32 v3, v6, v7
	global_store_dwordx4 v[10:11], v[0:3], off offset:2048 sc1
	ds_read_b128 v[0:3], v12 offset:8832
	ds_read_b128 v[4:7], v12 offset:8896
	s_waitcnt lgkmcnt(1)
	v_cvt_pk_bf16_f32 v0, v0, v1
	v_cvt_pk_bf16_f32 v1, v2, v3
	s_waitcnt lgkmcnt(0)
	v_cvt_pk_bf16_f32 v2, v4, v5
	v_cvt_pk_bf16_f32 v3, v6, v7
	global_store_dwordx4 v[10:11], v[0:3], off offset:3072 sc1
	ds_read_b128 v[0:3], v12 offset:13056
	ds_read_b128 v[4:7], v12 offset:13120
	v_add_co_u32_e32 v10, vcc, s12, v10
	s_waitcnt lgkmcnt(1)
	v_cvt_pk_bf16_f32 v0, v0, v1
	v_cvt_pk_bf16_f32 v1, v2, v3
	s_waitcnt lgkmcnt(0)
	v_cvt_pk_bf16_f32 v2, v4, v5
	v_cvt_pk_bf16_f32 v3, v6, v7
	v_addc_co_u32_e32 v11, vcc, 0, v11, vcc
	global_store_dwordx4 v[10:11], v[0:3], off sc1
	ds_read_b128 v[0:3], v12 offset:13184
	ds_read_b128 v[4:7], v12 offset:13248
	s_waitcnt lgkmcnt(1)
	v_cvt_pk_bf16_f32 v0, v0, v1
	v_cvt_pk_bf16_f32 v1, v2, v3
	s_waitcnt lgkmcnt(0)
	v_cvt_pk_bf16_f32 v2, v4, v5
	v_cvt_pk_bf16_f32 v3, v6, v7
	global_store_dwordx4 v[10:11], v[0:3], off offset:1024 sc1
	s_nop 1
	v_mov_b32_e32 v0, v23
.LBB0_860:
	v_lshlrev_b32_e32 v1, 5, v8
	v_or_b32_e32 v83, s84, v20
	v_add_u32_e32 v23, s93, v1
	v_add_u32_e32 v66, s88, v1
	v_mul_u32_u24_e32 v1, 0x48, v83
	v_lshlrev_b32_e32 v1, 1, v1
	v_lshl_add_u32 v0, v0, 2, v23
	v_add3_u32 v96, s63, v1, v21
	ds_read_b128 v[4:7], v0
	ds_read_b128 v[10:13], v0 offset:16
	ds_read_b128 v[26:29], v66 offset:47104
	ds_read_b128 v[30:33], v66 offset:47120
	ds_read_b128 v[18:21], v66 offset:46336
	ds_read_b128 v[14:17], v66 offset:46352
	v_mad_u32_u24 v93, v22, s73, v23
	s_waitcnt lgkmcnt(3)
	v_pk_mul_f32 v[2:3], v[6:7], v[28:29]
	v_pk_mul_f32 v[0:1], v[4:5], v[26:27]
	s_waitcnt lgkmcnt(2)
	v_pk_mul_f32 v[24:25], v[12:13], v[32:33]
	v_pk_mul_f32 v[34:35], v[10:11], v[30:31]
	v_cvt_pk_bf16_f32 v0, v0, v1
	v_cvt_pk_bf16_f32 v1, v2, v3
	v_cvt_pk_bf16_f32 v2, v34, v35
	v_cvt_pk_bf16_f32 v3, v24, v25
	ds_read_b128 v[34:37], v96 offset:53248
	ds_read_b128 v[38:41], v96 offset:62464
	ds_read_b128 v[22:25], v93
	ds_read_b128 v[42:45], v93 offset:16
	s_waitcnt lgkmcnt(5)
	v_pk_mul_f32 v[6:7], v[6:7], v[20:21]
	v_pk_mul_f32 v[4:5], v[4:5], v[18:19]
	s_waitcnt lgkmcnt(4)
	v_pk_mul_f32 v[12:13], v[12:13], v[16:17]
	v_pk_mul_f32 v[10:11], v[10:11], v[14:15]
	v_cvt_pk_bf16_f32 v4, v4, v5
	v_cvt_pk_bf16_f32 v5, v6, v7
	v_cvt_pk_bf16_f32 v6, v10, v11
	v_cvt_pk_bf16_f32 v7, v12, v13
	s_waitcnt lgkmcnt(1)
	v_pk_mul_f32 v[12:13], v[28:29], v[24:25]
	v_pk_mul_f32 v[10:11], v[26:27], v[22:23]
	s_waitcnt lgkmcnt(0)
	v_pk_mul_f32 v[46:47], v[32:33], v[44:45]
	v_pk_mul_f32 v[48:49], v[30:31], v[42:43]
	v_pk_mul_f32 v[24:25], v[20:21], v[24:25]
	v_pk_mul_f32 v[22:23], v[18:19], v[22:23]
	v_pk_mul_f32 v[44:45], v[16:17], v[44:45]
	v_pk_mul_f32 v[42:43], v[14:15], v[42:43]
	v_cvt_pk_bf16_f32 v10, v10, v11
	v_cvt_pk_bf16_f32 v11, v12, v13
	v_cvt_pk_bf16_f32 v12, v48, v49
	v_cvt_pk_bf16_f32 v13, v46, v47
	v_cvt_pk_bf16_f32 v22, v22, v23
	v_cvt_pk_bf16_f32 v23, v24, v25
	v_cvt_pk_bf16_f32 v24, v42, v43
	v_cvt_pk_bf16_f32 v25, v44, v45
	ds_read_b128 v[42:45], v93 offset:4352
	ds_read_b128 v[46:49], v93 offset:4368
	v_mfma_f32_16x16x32_bf16 v[0:3], v[0:3], v[34:37], 0
	s_ashr_i32 s12, s31, 2
	s_and_b32 s14, s30, 6
	s_waitcnt lgkmcnt(1)
	v_pk_mul_f32 v[52:53], v[28:29], v[44:45]
	v_pk_mul_f32 v[50:51], v[26:27], v[42:43]
	s_waitcnt lgkmcnt(0)
	v_pk_mul_f32 v[54:55], v[32:33], v[48:49]
	v_pk_mul_f32 v[56:57], v[30:31], v[46:47]
	v_pk_mul_f32 v[44:45], v[20:21], v[44:45]
	v_pk_mul_f32 v[42:43], v[18:19], v[42:43]
	v_pk_mul_f32 v[48:49], v[16:17], v[48:49]
	v_pk_mul_f32 v[46:47], v[14:15], v[46:47]
	v_cvt_pk_bf16_f32 v50, v50, v51
	v_cvt_pk_bf16_f32 v51, v52, v53
	v_cvt_pk_bf16_f32 v52, v56, v57
	v_cvt_pk_bf16_f32 v53, v54, v55
	v_cvt_pk_bf16_f32 v42, v42, v43
	v_cvt_pk_bf16_f32 v43, v44, v45
	v_cvt_pk_bf16_f32 v44, v46, v47
	v_cvt_pk_bf16_f32 v45, v48, v49
	v_mfma_f32_16x16x32_bf16 v[58:61], v[50:53], v[34:37], 0
	s_ashr_i32 s13, s12, 31
	s_add_i32 s82, s14, s85
	s_lshl_b64 s[12:13], s[12:13], 15
	v_mfma_f32_16x16x32_bf16 v[62:65], v[42:45], v[38:41], 0
	ds_read_b128 v[74:77], v93 offset:4480
	ds_read_b128 v[70:73], v93 offset:4496
	ds_read_b128 v[54:57], v66 offset:47232
	ds_read_b128 v[50:53], v66 offset:47248
	ds_read_b128 v[46:49], v66 offset:46464
	ds_read_b128 v[42:45], v66 offset:46480
	s_lshl_b64 s[14:15], s[82:83], 12
	s_waitcnt lgkmcnt(3)
	v_pk_mul_f32 v[66:67], v[76:77], v[56:57]
	v_pk_mul_f32 v[68:69], v[74:75], v[54:55]
	s_waitcnt lgkmcnt(2)
	v_pk_mul_f32 v[94:95], v[72:73], v[52:53]
	v_pk_mul_f32 v[80:81], v[70:71], v[50:51]
	s_waitcnt lgkmcnt(1)
	v_pk_mul_f32 v[76:77], v[76:77], v[48:49]
	v_pk_mul_f32 v[74:75], v[74:75], v[46:47]
	s_waitcnt lgkmcnt(0)
	v_pk_mul_f32 v[72:73], v[72:73], v[44:45]
	v_pk_mul_f32 v[70:71], v[70:71], v[42:43]
	v_cvt_pk_bf16_f32 v78, v68, v69
	v_cvt_pk_bf16_f32 v79, v66, v67
	v_cvt_pk_bf16_f32 v80, v80, v81
	v_cvt_pk_bf16_f32 v81, v94, v95
	ds_read_b128 v[66:69], v96 offset:53312
	v_cvt_pk_bf16_f32 v74, v74, v75
	v_cvt_pk_bf16_f32 v75, v76, v77
	v_cvt_pk_bf16_f32 v76, v70, v71
	v_cvt_pk_bf16_f32 v77, v72, v73
	ds_read_b128 v[70:73], v96 offset:62528
	s_waitcnt lgkmcnt(1)
	v_mfma_f32_16x16x32_bf16 v[58:61], v[78:81], v[66:69], v[58:61]
	s_add_u32 s12, s12, s14
	s_addc_u32 s13, s13, s15
	v_cmp_eq_u32_e32 vcc, v87, v83
	s_waitcnt lgkmcnt(0)
	v_mfma_f32_16x16x32_bf16 v[62:65], v[74:77], v[70:73], v[62:65]
	ds_read_b128 v[74:77], v93 offset:8704
	ds_read_b128 v[78:81], v93 offset:8720
	s_lshl_b64 s[14:15], s[12:13], 2
	s_add_u32 s12, s6, s14
	v_mfma_f32_16x16x32_bf16 v[4:7], v[4:7], v[38:41], 0
	s_waitcnt lgkmcnt(1)
	v_pk_mul_f32 v[28:29], v[28:29], v[76:77]
	v_pk_mul_f32 v[26:27], v[26:27], v[74:75]
	s_waitcnt lgkmcnt(0)
	v_pk_mul_f32 v[30:31], v[30:31], v[78:79]
	v_pk_mul_f32 v[32:33], v[32:33], v[80:81]
	v_cvt_pk_bf16_f32 v26, v26, v27
	v_cvt_pk_bf16_f32 v27, v28, v29
	v_cvt_pk_bf16_f32 v28, v30, v31
	v_pk_mul_f32 v[20:21], v[20:21], v[76:77]
	v_pk_mul_f32 v[18:19], v[18:19], v[74:75]
	v_pk_mul_f32 v[30:31], v[16:17], v[80:81]
	v_pk_mul_f32 v[16:17], v[14:15], v[78:79]
	v_cvt_pk_bf16_f32 v29, v32, v33
	v_cvt_pk_bf16_f32 v14, v18, v19
	v_cvt_pk_bf16_f32 v15, v20, v21
	v_cvt_pk_bf16_f32 v16, v16, v17
	v_cvt_pk_bf16_f32 v17, v30, v31
	ds_read_b128 v[18:21], v93 offset:8832
	ds_read_b128 v[30:33], v93 offset:8848
	v_mfma_f32_16x16x32_bf16 v[10:13], v[10:13], v[34:37], 0
	s_addc_u32 s13, s7, s15
	v_readlane_b32 s28, v252, 36
	s_add_u32 s14, s8, s14
	v_mfma_f32_16x16x32_bf16 v[22:25], v[22:25], v[38:41], 0
	s_addc_u32 s15, s9, s15
	v_mfma_f32_16x16x32_bf16 v[26:29], v[26:29], v[34:37], 0
	s_waitcnt lgkmcnt(1)
	v_pk_mul_f32 v[36:37], v[56:57], v[20:21]
	v_pk_mul_f32 v[34:35], v[54:55], v[18:19]
	v_pk_mul_f32 v[20:21], v[48:49], v[20:21]
	v_mfma_f32_16x16x32_bf16 v[14:17], v[14:17], v[38:41], 0
	s_waitcnt lgkmcnt(0)
	v_pk_mul_f32 v[38:39], v[52:53], v[32:33]
	v_pk_mul_f32 v[40:41], v[50:51], v[30:31]
	v_pk_mul_f32 v[18:19], v[46:47], v[18:19]
	v_pk_mul_f32 v[32:33], v[44:45], v[32:33]
	v_pk_mul_f32 v[30:31], v[42:43], v[30:31]
	v_cvt_pk_bf16_f32 v18, v18, v19
	v_cvt_pk_bf16_f32 v19, v20, v21
	v_cvt_pk_bf16_f32 v20, v30, v31
	v_cvt_pk_bf16_f32 v21, v32, v33
	v_cvt_pk_bf16_f32 v34, v34, v35
	v_cvt_pk_bf16_f32 v35, v36, v37
	v_mfma_f32_16x16x32_bf16 v[14:17], v[18:21], v[70:73], v[14:17]
	ds_read_b128 v[18:21], v92 offset:47360
	v_cvt_pk_bf16_f32 v36, v40, v41
	v_cvt_pk_bf16_f32 v37, v38, v39
	s_waitcnt lgkmcnt(0)
	v_pk_mul_f32 v[30:31], v[2:3], v[20:21]
	v_pk_mul_f32 v[32:33], v[0:1], v[18:19]
	ds_read_b128 v[0:3], v92 offset:47424
	v_pk_mul_f32 v[6:7], v[6:7], v[20:21]
	v_pk_mul_f32 v[4:5], v[4:5], v[18:19]
	v_mfma_f32_16x16x32_bf16 v[26:29], v[34:37], v[66:69], v[26:29]
	v_cvt_pk_bf16_f32 v4, v4, v5
	s_waitcnt lgkmcnt(0)
	v_pk_mul_f32 v[12:13], v[12:13], v[2:3]
	v_pk_mul_f32 v[10:11], v[10:11], v[0:1]
	v_pk_mul_f32 v[18:19], v[24:25], v[2:3]
	v_pk_mul_f32 v[20:21], v[22:23], v[0:1]
	ds_read_b128 v[0:3], v92 offset:47488
	v_cvt_pk_bf16_f32 v5, v6, v7
	v_cvt_pk_bf16_f32 v7, v18, v19
	v_mov_b32_e32 v18, s88
	ds_read_b32 v18, v18 offset:46332
	s_waitcnt lgkmcnt(1)
	v_pk_mul_f32 v[22:23], v[60:61], v[2:3]
	v_pk_mul_f32 v[24:25], v[58:59], v[0:1]
	v_pk_mul_f32 v[34:35], v[64:65], v[2:3]
	v_pk_mul_f32 v[36:37], v[62:63], v[0:1]
	ds_read_b128 v[0:3], v92 offset:47552
	v_cvt_pk_bf16_f32 v6, v20, v21
	s_waitcnt lgkmcnt(1)
	v_mul_f32_e32 v18, 0x3fb8aa3b, v18
	v_add3_u32 v21, s63, v84, v91
	v_exp_f32_e32 v20, v18
	s_waitcnt lgkmcnt(0)
	v_pk_mul_f32 v[28:29], v[28:29], v[2:3]
	v_pk_mul_f32 v[26:27], v[26:27], v[0:1]
	v_add_u32_e32 v18, 0xd000, v21
	v_pk_mul_f32 v[38:39], v[16:17], v[2:3]
	v_cvt_pk_bf16_f32 v16, v10, v11
	v_cvt_pk_bf16_f32 v17, v12, v13
	v_cvt_pk_bf16_f32 v10, v24, v25
	v_cvt_pk_bf16_f32 v11, v22, v23
	v_cvt_pk_bf16_f32 v12, v26, v27
	v_cvt_pk_bf16_f32 v13, v28, v29
	ds_read2_b64 v[22:25], v18 offset1:4
	ds_read2_b64 v[26:29], v18 offset0:8 offset1:12
	v_pk_mul_f32 v[2:3], v[14:15], v[0:1]
	v_cvt_pk_bf16_f32 v14, v32, v33
	v_cvt_pk_bf16_f32 v15, v30, v31
	v_cndmask_b32_e32 v18, 0, v20, vcc
	v_cvt_pk_bf16_f32 v0, v36, v37
	s_waitcnt lgkmcnt(1)
	v_mfma_f32_16x16x32_bf16 v[30:33], v[22:25], v[14:17], 0
	v_cvt_pk_bf16_f32 v1, v34, v35
	v_cvt_pk_bf16_f32 v2, v2, v3
	v_cvt_pk_bf16_f32 v3, v38, v39
	s_waitcnt lgkmcnt(0)
	v_mfma_f32_16x16x32_bf16 v[30:33], v[26:29], v[10:13], v[30:33]
	v_mfma_f32_16x16x32_bf16 v[22:25], v[22:25], v[4:7], 0
	v_mfma_f32_16x16x32_bf16 v[22:25], v[26:29], v[0:3], v[22:25]
	s_nop 5
	v_sub_f32_e32 v30, v18, v30
	v_lshl_or_b32 v18, v8, 8, v83
	v_ashrrev_i32_e32 v19, 31, v18
	v_or_b32_e32 v8, 1, v87
	v_lshl_add_u64 v[18:19], v[18:19], 2, s[12:13]
	v_cmp_eq_u32_e32 vcc, v8, v83
	global_store_dword v[18:19], v30, off sc1
	s_nop 0
	v_cndmask_b32_e32 v18, 0, v20, vcc
	v_sub_f32_e32 v30, v18, v31
	v_lshl_or_b32 v18, v8, 6, v83
	v_ashrrev_i32_e32 v19, 31, v18
	v_lshl_add_u64 v[18:19], v[18:19], 2, s[12:13]
	global_store_dword v[18:19], v30, off sc1
	v_cmp_eq_u32_e32 vcc, v90, v83
	v_lshl_or_b32 v18, v90, 6, v83
	v_ashrrev_i32_e32 v19, 31, v18
	v_cndmask_b32_e32 v8, 0, v20, vcc
	v_sub_f32_e32 v8, v8, v32
	v_lshl_add_u64 v[18:19], v[18:19], 2, s[12:13]
	global_store_dword v[18:19], v8, off sc1
	v_cmp_eq_u32_e32 vcc, v89, v83
	v_lshl_or_b32 v18, v89, 6, v83
	v_ashrrev_i32_e32 v19, 31, v18
	v_cndmask_b32_e32 v8, 0, v20, vcc
	v_sub_f32_e32 v8, v8, v33
	v_lshl_add_u64 v[18:19], v[18:19], 2, s[12:13]
	global_store_dword v[18:19], v8, off sc1
	v_lshl_add_u32 v18, v82, 2, s28
	v_ashrrev_i32_e32 v19, 31, v18
	v_lshl_add_u64 v[18:19], v[18:19], 2, s[14:15]
	global_store_dwordx4 v[18:19], v[22:25], off sc1
	v_add_u32_e32 v8, 0xd800, v21
	ds_read2_b64 v[22:25], v8 offset0:32 offset1:36
	ds_read2_b64 v[26:29], v8 offset0:40 offset1:44
	s_waitcnt lgkmcnt(1)
	v_mfma_f32_16x16x32_bf16 v[30:33], v[22:25], v[14:17], 0
	v_add_u32_e32 v8, 16, v87
	v_cmp_eq_u32_e32 vcc, v8, v83
	s_waitcnt lgkmcnt(0)
	v_mfma_f32_16x16x32_bf16 v[30:33], v[26:29], v[10:13], v[30:33]
	v_cndmask_b32_e32 v34, 0, v20, vcc
	v_mfma_f32_16x16x32_bf16 v[22:25], v[22:25], v[4:7], 0
	v_mfma_f32_16x16x32_bf16 v[22:25], v[26:29], v[0:3], v[22:25]
	s_nop 4
	v_sub_f32_e32 v30, v34, v30
	v_lshl_or_b32 v34, v8, 6, v83
	v_ashrrev_i32_e32 v35, 31, v34
	v_add_u32_e32 v8, 17, v87
	v_lshl_add_u64 v[34:35], v[34:35], 2, s[12:13]
	v_cmp_eq_u32_e32 vcc, v8, v83
	global_store_dword v[34:35], v30, off sc1
	s_nop 0
	v_cndmask_b32_e32 v30, 0, v20, vcc
	v_sub_f32_e32 v34, v30, v31
	v_lshl_or_b32 v30, v8, 6, v83
	v_ashrrev_i32_e32 v31, 31, v30
	v_add_u32_e32 v8, 18, v87
	v_lshl_add_u64 v[30:31], v[30:31], 2, s[12:13]
	v_cmp_eq_u32_e32 vcc, v8, v83
	global_store_dword v[30:31], v34, off sc1
	s_nop 0
	v_cndmask_b32_e32 v30, 0, v20, vcc
	v_sub_f32_e32 v32, v30, v32
	v_lshl_or_b32 v30, v8, 6, v83
	v_ashrrev_i32_e32 v31, 31, v30
	v_add_u32_e32 v8, 19, v87
	v_lshl_add_u64 v[30:31], v[30:31], 2, s[12:13]
	v_cmp_eq_u32_e32 vcc, v8, v83
	global_store_dword v[30:31], v32, off sc1
	s_nop 0
	v_cndmask_b32_e32 v30, 0, v20, vcc
	v_sub_f32_e32 v32, v30, v33
	v_lshl_or_b32 v30, v8, 6, v83
	v_ashrrev_i32_e32 v31, 31, v30
	v_lshl_add_u64 v[30:31], v[30:31], 2, s[12:13]
	global_store_dword v[30:31], v32, off sc1
	global_store_dwordx4 v[18:19], v[22:25], off offset:1024 sc1
	v_add_u32_e32 v8, 0xe000, v21
	ds_read2_b64 v[22:25], v8 offset0:64 offset1:68
	ds_read2_b64 v[26:29], v8 offset0:72 offset1:76
	s_waitcnt lgkmcnt(1)
	v_mfma_f32_16x16x32_bf16 v[30:33], v[22:25], v[14:17], 0
	v_add_u32_e32 v8, 32, v87
	v_cmp_eq_u32_e32 vcc, v8, v83
	s_waitcnt lgkmcnt(0)
	v_mfma_f32_16x16x32_bf16 v[30:33], v[26:29], v[10:13], v[30:33]
	v_cndmask_b32_e32 v34, 0, v20, vcc
	v_mfma_f32_16x16x32_bf16 v[22:25], v[22:25], v[4:7], 0
	v_mfma_f32_16x16x32_bf16 v[22:25], v[26:29], v[0:3], v[22:25]
	s_nop 4
	v_sub_f32_e32 v30, v34, v30
	v_lshl_or_b32 v34, v8, 6, v83
	v_ashrrev_i32_e32 v35, 31, v34
	v_add_u32_e32 v8, 33, v87
	v_lshl_add_u64 v[34:35], v[34:35], 2, s[12:13]
	v_cmp_eq_u32_e32 vcc, v8, v83
	global_store_dword v[34:35], v30, off sc1
	s_nop 0
	v_cndmask_b32_e32 v30, 0, v20, vcc
	v_sub_f32_e32 v34, v30, v31
	v_lshl_or_b32 v30, v8, 6, v83
	v_ashrrev_i32_e32 v31, 31, v30
	v_add_u32_e32 v8, 34, v87
	v_lshl_add_u64 v[30:31], v[30:31], 2, s[12:13]
	v_cmp_eq_u32_e32 vcc, v8, v83
	global_store_dword v[30:31], v34, off sc1
	s_nop 0
	v_cndmask_b32_e32 v30, 0, v20, vcc
	v_sub_f32_e32 v32, v30, v32
	v_lshl_or_b32 v30, v8, 6, v83
	v_ashrrev_i32_e32 v31, 31, v30
	v_add_u32_e32 v8, 35, v87
	v_lshl_add_u64 v[30:31], v[30:31], 2, s[12:13]
	v_cmp_eq_u32_e32 vcc, v8, v83
	global_store_dword v[30:31], v32, off sc1
	s_nop 0
	v_cndmask_b32_e32 v30, 0, v20, vcc
	v_sub_f32_e32 v32, v30, v33
	v_lshl_or_b32 v30, v8, 6, v83
	v_ashrrev_i32_e32 v31, 31, v30
	v_lshl_add_u64 v[30:31], v[30:31], 2, s[12:13]
	global_store_dword v[30:31], v32, off sc1
	global_store_dwordx4 v[18:19], v[22:25], off offset:2048 sc1
	v_add_u32_e32 v8, 0xe800, v21
	ds_read2_b64 v[22:25], v8 offset0:96 offset1:100
	ds_read2_b64 v[26:29], v8 offset0:104 offset1:108
	s_waitcnt lgkmcnt(1)
	v_mfma_f32_16x16x32_bf16 v[14:17], v[22:25], v[14:17], 0
	v_cmp_eq_u32_e32 vcc, v88, v83
	s_waitcnt lgkmcnt(0)
	v_mfma_f32_16x16x32_bf16 v[10:13], v[26:29], v[10:13], v[14:17]
	v_cndmask_b32_e32 v8, 0, v20, vcc
	s_nop 3
	v_lshl_or_b32 v14, v88, 6, v83
	v_ashrrev_i32_e32 v15, 31, v14
	s_nop 0
	v_sub_f32_e32 v8, v8, v10
	v_lshl_add_u64 v[14:15], v[14:15], 2, s[12:13]
	global_store_dword v[14:15], v8, off sc1
	v_add_u32_e32 v8, 49, v87
	v_cmp_eq_u32_e32 vcc, v8, v83
	v_mfma_f32_16x16x32_bf16 v[4:7], v[22:25], v[4:7], 0
	s_nop 0
	v_cndmask_b32_e32 v10, 0, v20, vcc
	v_sub_f32_e32 v14, v10, v11
	v_lshl_or_b32 v10, v8, 6, v83
	v_ashrrev_i32_e32 v11, 31, v10
	v_lshl_add_u64 v[10:11], v[10:11], 2, s[12:13]
	global_store_dword v[10:11], v14, off sc1
	v_cmp_eq_u32_e32 vcc, v86, v83
	v_lshl_or_b32 v10, v86, 6, v83
	v_ashrrev_i32_e32 v11, 31, v10
	v_cndmask_b32_e32 v8, 0, v20, vcc
	v_sub_f32_e32 v8, v8, v12
	v_lshl_add_u64 v[10:11], v[10:11], 2, s[12:13]
	global_store_dword v[10:11], v8, off sc1
	v_lshl_or_b32 v10, v85, 6, v83
	v_ashrrev_i32_e32 v11, 31, v10
	v_lshl_add_u64 v[10:11], v[10:11], 2, s[12:13]
	v_readlane_b32 s12, v253, 22
	s_add_i32 s30, s30, s12
	v_mfma_f32_16x16x32_bf16 v[0:3], v[26:29], v[0:3], v[4:7]
	s_add_u32 s10, s10, s60
	v_cmp_eq_u32_e32 vcc, v85, v83
	s_addc_u32 s11, s11, s57
	v_readlane_b32 s12, v254, 46
	v_cndmask_b32_e32 v8, 0, v20, vcc
	v_readlane_b32 s13, v254, 47
	s_add_u32 s24, s24, s12
	v_sub_f32_e32 v8, v8, v13
	s_addc_u32 s25, s25, s13
	s_andn2_b64 vcc, exec, s[26:27]
	global_store_dword v[10:11], v8, off sc1
	global_store_dwordx4 v[18:19], v[0:3], off offset:3072 sc1
	s_barrier
	s_cbranch_vccz .LBB0_862
	s_mov_b32 s31, s34
	s_branch .LBB0_812

.LBB0_890:
	s_andn2_saveexec_b64 s[8:9], s[12:13]
	s_cbranch_execz .LBB0_906
	s_add_i32 s101, s101, 1
	v_mov_b32_e32 v1, s54
	v_add_co_u32_e32 v2, vcc, 0x3000, v1
	v_mov_b32_e32 v1, s55
	s_nop 0
	s_waitcnt vmcnt(0)
	v_addc_co_u32_e32 v3, vcc, 0, v1, vcc
	flat_atomic_add v1, v[2:3], v228 offset:1024 sc0
	v_cvt_f32_u32_e32 v2, v0
	v_sub_u32_e32 v3, 0, v0
	s_add_u32 s12, s54, 0x3400
	s_addc_u32 s13, s55, 0
	v_rcp_iflag_f32_e32 v2, v2
	s_mov_b64 s[16:17], -1
	v_mul_f32_e32 v2, 0x4f7ffffe, v2
	v_cvt_u32_f32_e32 v2, v2
	v_mul_lo_u32 v3, v3, v2
	v_mul_hi_u32 v3, v2, v3
	v_add_u32_e32 v2, v2, v3
	s_waitcnt vmcnt(0) lgkmcnt(0)
	v_mul_hi_u32 v2, v1, v2
	v_mul_lo_u32 v3, v2, v0
	v_sub_u32_e32 v3, v1, v3
	v_cmp_ge_u32_e32 vcc, v3, v0
	v_add_u32_e32 v4, 1, v2
	s_nop 0
	v_cndmask_b32_e32 v2, v2, v4, vcc
	v_sub_u32_e32 v4, v3, v0
	v_cndmask_b32_e32 v3, v3, v4, vcc
	v_cmp_ge_u32_e32 vcc, v3, v0
	v_add_u32_e32 v3, 1, v2
	s_nop 0
	v_cndmask_b32_e32 v2, v2, v3, vcc
	v_add_u32_e32 v3, 1, v1
	v_mad_u64_u32 v[0:1], s[8:9], v0, v2, v[0:1]
	v_cmp_ne_u32_e32 vcc, v3, v0
	v_mov_b32_e32 v3, v0
	v_mov_b64_e32 v[0:1], s[12:13]
	s_and_saveexec_b64 s[14:15], vcc
	s_cbranch_execz .LBB0_903
	v_mov_b64_e32 v[0:1], s[12:13]
	flat_load_dword v0, v[0:1] sc1
	s_mov_b64 s[20:21], 0
	s_waitcnt vmcnt(0) lgkmcnt(0)
	v_cmp_lt_u32_e32 vcc, v0, v3
	s_and_saveexec_b64 s[18:19], vcc
	s_cbranch_execz .LBB0_902
	s_add_u32 s16, s54, 0x200
	s_addc_u32 s17, s55, 0
	s_mov_b32 s7, 1
	s_branch .LBB0_895

.LBB0_995:
	s_waitcnt vmcnt(0)
	v_mfma_f32_16x16x4_f32 v[70:73], v54, v0, v[70:73]
	s_and_b64 s[14:15], s[90:91], exec
	s_cselect_b32 s14, s22, s18
	s_add_i32 s14, s14, s11
	s_ashr_i32 s15, s14, 31
	s_lshl_b64 s[14:15], s[14:15], 17
	s_or_b32 s14, s14, s21
	s_cmp_eq_u32 s24, -1
	v_mfma_f32_16x16x4_f32 v[74:77], v66, v0, v[74:77]
	v_mfma_f32_16x16x4_f32 v[90:93], v82, v0, v[90:93]
	v_mfma_f32_16x16x4_f32 v[110:113], v86, v0, v[110:113]
	v_mfma_f32_16x16x4_f32 v[70:73], v55, v1, v[70:73]
	v_mfma_f32_16x16x4_f32 v[74:77], v67, v1, v[74:77]
	v_mfma_f32_16x16x4_f32 v[90:93], v83, v1, v[90:93]
	v_mfma_f32_16x16x4_f32 v[110:113], v87, v1, v[110:113]
	v_mfma_f32_16x16x4_f32 v[70:73], v56, v2, v[70:73]
	v_mfma_f32_16x16x4_f32 v[74:77], v68, v2, v[74:77]
	v_mfma_f32_16x16x4_f32 v[90:93], v84, v2, v[90:93]
	v_mfma_f32_16x16x4_f32 v[110:113], v88, v2, v[110:113]
	v_mfma_f32_16x16x4_f32 v[54:57], v57, v3, v[70:73]
	v_mfma_f32_16x16x4_f32 v[66:69], v69, v3, v[74:77]
	v_mfma_f32_16x16x4_f32 v[70:73], v85, v3, v[90:93]
	v_mfma_f32_16x16x4_f32 v[74:77], v89, v3, v[110:113]
	v_mfma_f32_16x16x4_f32 v[54:57], v42, v10, v[54:57]
	v_mfma_f32_16x16x4_f32 v[66:69], v50, v10, v[66:69]
	v_mfma_f32_16x16x4_f32 v[70:73], v62, v10, v[70:73]
	v_mfma_f32_16x16x4_f32 v[74:77], v78, v10, v[74:77]
	v_mfma_f32_16x16x4_f32 v[54:57], v43, v11, v[54:57]
	v_mfma_f32_16x16x4_f32 v[66:69], v51, v11, v[66:69]
	v_mfma_f32_16x16x4_f32 v[70:73], v63, v11, v[70:73]
	v_mfma_f32_16x16x4_f32 v[74:77], v79, v11, v[74:77]
	v_mfma_f32_16x16x4_f32 v[54:57], v44, v12, v[54:57]
	v_mfma_f32_16x16x4_f32 v[66:69], v52, v12, v[66:69]
	v_mfma_f32_16x16x4_f32 v[70:73], v64, v12, v[70:73]
	v_mfma_f32_16x16x4_f32 v[74:77], v80, v12, v[74:77]
	v_mfma_f32_16x16x4_f32 v[42:45], v45, v13, v[54:57]
	v_mfma_f32_16x16x4_f32 v[50:53], v53, v13, v[66:69]
	v_mfma_f32_16x16x4_f32 v[54:57], v65, v13, v[70:73]
	v_mfma_f32_16x16x4_f32 v[62:65], v81, v13, v[74:77]
	v_mfma_f32_16x16x4_f32 v[42:45], v26, v14, v[42:45]
	v_mfma_f32_16x16x4_f32 v[50:53], v38, v14, v[50:53]
	v_mfma_f32_16x16x4_f32 v[54:57], v46, v14, v[54:57]
	v_mfma_f32_16x16x4_f32 v[62:65], v58, v14, v[62:65]
	v_mfma_f32_16x16x4_f32 v[42:45], v27, v15, v[42:45]
	v_mfma_f32_16x16x4_f32 v[50:53], v39, v15, v[50:53]
	v_mfma_f32_16x16x4_f32 v[54:57], v47, v15, v[54:57]
	v_mfma_f32_16x16x4_f32 v[62:65], v59, v15, v[62:65]
	v_mfma_f32_16x16x4_f32 v[42:45], v28, v16, v[42:45]
	v_mfma_f32_16x16x4_f32 v[50:53], v40, v16, v[50:53]
	v_mfma_f32_16x16x4_f32 v[54:57], v48, v16, v[54:57]
	v_mfma_f32_16x16x4_f32 v[62:65], v60, v16, v[62:65]
	v_mfma_f32_16x16x4_f32 v[26:29], v29, v17, v[42:45]
	v_mfma_f32_16x16x4_f32 v[38:41], v41, v17, v[50:53]
	v_mfma_f32_16x16x4_f32 v[42:45], v49, v17, v[54:57]
	v_mfma_f32_16x16x4_f32 v[46:49], v61, v17, v[62:65]
	v_mfma_f32_16x16x4_f32 v[26:29], v4, v18, v[26:29]
	v_mfma_f32_16x16x4_f32 v[38:41], v22, v18, v[38:41]
	v_mfma_f32_16x16x4_f32 v[42:45], v30, v18, v[42:45]
	v_mfma_f32_16x16x4_f32 v[46:49], v34, v18, v[46:49]
	v_mfma_f32_16x16x4_f32 v[26:29], v5, v19, v[26:29]
	v_lshl_add_u64 v[4:5], v[228:229], 0, s[14:15]
	global_store_dwordx4 v[4:5], v[0:3], off sc1
	global_store_dwordx4 v[4:5], v[10:13], off offset:1024 sc1
	global_store_dwordx4 v[4:5], v[14:17], off offset:2048 sc1
	global_store_dwordx4 v[4:5], v[18:21], off offset:3072 sc1
	v_mfma_f32_16x16x4_f32 v[38:41], v23, v19, v[38:41]
	v_mfma_f32_16x16x4_f32 v[42:45], v31, v19, v[42:45]
	v_mfma_f32_16x16x4_f32 v[46:49], v35, v19, v[46:49]
	v_mfma_f32_16x16x4_f32 v[26:29], v6, v20, v[26:29]
	v_mfma_f32_16x16x4_f32 v[38:41], v24, v20, v[38:41]
	v_mfma_f32_16x16x4_f32 v[42:45], v32, v20, v[42:45]
	v_mfma_f32_16x16x4_f32 v[46:49], v36, v20, v[46:49]
	v_mfma_f32_16x16x4_f32 v[0:3], v7, v21, v[26:29]
	v_mfma_f32_16x16x4_f32 v[10:13], v25, v21, v[38:41]
	v_mfma_f32_16x16x4_f32 v[14:17], v33, v21, v[42:45]
	v_mfma_f32_16x16x4_f32 v[18:21], v37, v21, v[46:49]
	s_cbranch_scc1 .LBB0_997
	v_mov_b64_e32 v[34:35], v[154:155]
	v_mov_b64_e32 v[58:59], v[158:159]
	v_mov_b64_e32 v[78:79], v[162:163]
	v_mov_b64_e32 v[86:87], v[166:167]
	v_mov_b64_e32 v[30:31], v[150:151]
	v_mov_b64_e32 v[46:47], v[138:139]
	v_mov_b64_e32 v[62:63], v[142:143]
	v_mov_b64_e32 v[82:83], v[146:147]
	v_mov_b64_e32 v[22:23], v[118:119]
	v_mov_b64_e32 v[38:39], v[122:123]
	v_mov_b64_e32 v[50:51], v[126:127]
	v_mov_b64_e32 v[66:67], v[130:131]
	v_mov_b64_e32 v[4:5], v[106:107]
	v_mov_b64_e32 v[26:27], v[94:95]
	v_mov_b64_e32 v[42:43], v[98:99]
	v_mov_b64_e32 v[54:55], v[102:103]
	v_mov_b64_e32 v[110:111], v[174:175]
	v_mov_b64_e32 v[90:91], v[170:171]
	v_mov_b64_e32 v[74:75], v[134:135]
	v_mov_b64_e32 v[70:71], v[114:115]
	s_mov_b32 s18, s24
	v_mov_b64_e32 v[36:37], v[156:157]
	v_mov_b64_e32 v[60:61], v[160:161]
	v_mov_b64_e32 v[80:81], v[164:165]
	v_mov_b64_e32 v[88:89], v[168:169]
	v_mov_b64_e32 v[32:33], v[152:153]
	v_mov_b64_e32 v[48:49], v[140:141]
	v_mov_b64_e32 v[64:65], v[144:145]
	v_mov_b64_e32 v[84:85], v[148:149]
	v_mov_b64_e32 v[24:25], v[120:121]
	v_mov_b64_e32 v[40:41], v[124:125]
	v_mov_b64_e32 v[52:53], v[128:129]
	v_mov_b64_e32 v[68:69], v[132:133]
	v_mov_b64_e32 v[6:7], v[108:109]
	v_mov_b64_e32 v[28:29], v[96:97]
	v_mov_b64_e32 v[44:45], v[100:101]
	v_mov_b64_e32 v[56:57], v[104:105]
	v_mov_b64_e32 v[112:113], v[176:177]
	v_mov_b64_e32 v[92:93], v[172:173]
	v_mov_b64_e32 v[76:77], v[136:137]
	v_mov_b64_e32 v[72:73], v[116:117]
	s_mov_b32 s22, s23
	s_add_i32 s23, s22, 1
	s_cmp_lt_u32 s23, s10
	s_mov_b64 s[14:15], -1
	s_cbranch_scc0 .LBB0_992
	s_branch .LBB0_993

.LBB0_1104:
	s_waitcnt vmcnt(0)
	v_mfma_f32_16x16x4_f32 v[70:73], v54, v0, v[70:73]
	s_and_b64 s[16:17], s[90:91], exec
	s_cselect_b32 s13, s21, s13
	s_add_i32 s16, s13, s11
	s_ashr_i32 s17, s16, 31
	s_lshl_b64 s[16:17], s[16:17], 17
	s_or_b32 s16, s16, s20
	s_cmp_eq_u32 s23, -1
	v_mfma_f32_16x16x4_f32 v[74:77], v66, v0, v[74:77]
	v_mfma_f32_16x16x4_f32 v[90:93], v82, v0, v[90:93]
	v_mfma_f32_16x16x4_f32 v[110:113], v86, v0, v[110:113]
	v_mfma_f32_16x16x4_f32 v[70:73], v55, v1, v[70:73]
	v_mfma_f32_16x16x4_f32 v[74:77], v67, v1, v[74:77]
	v_mfma_f32_16x16x4_f32 v[90:93], v83, v1, v[90:93]
	v_mfma_f32_16x16x4_f32 v[110:113], v87, v1, v[110:113]
	v_mfma_f32_16x16x4_f32 v[70:73], v56, v2, v[70:73]
	v_mfma_f32_16x16x4_f32 v[74:77], v68, v2, v[74:77]
	v_mfma_f32_16x16x4_f32 v[90:93], v84, v2, v[90:93]
	v_mfma_f32_16x16x4_f32 v[110:113], v88, v2, v[110:113]
	v_mfma_f32_16x16x4_f32 v[54:57], v57, v3, v[70:73]
	v_mfma_f32_16x16x4_f32 v[66:69], v69, v3, v[74:77]
	v_mfma_f32_16x16x4_f32 v[70:73], v85, v3, v[90:93]
	v_mfma_f32_16x16x4_f32 v[74:77], v89, v3, v[110:113]
	v_mfma_f32_16x16x4_f32 v[54:57], v42, v10, v[54:57]
	v_mfma_f32_16x16x4_f32 v[66:69], v50, v10, v[66:69]
	v_mfma_f32_16x16x4_f32 v[70:73], v62, v10, v[70:73]
	v_mfma_f32_16x16x4_f32 v[74:77], v78, v10, v[74:77]
	v_mfma_f32_16x16x4_f32 v[54:57], v43, v11, v[54:57]
	v_mfma_f32_16x16x4_f32 v[66:69], v51, v11, v[66:69]
	v_mfma_f32_16x16x4_f32 v[70:73], v63, v11, v[70:73]
	v_mfma_f32_16x16x4_f32 v[74:77], v79, v11, v[74:77]
	v_mfma_f32_16x16x4_f32 v[54:57], v44, v12, v[54:57]
	v_mfma_f32_16x16x4_f32 v[66:69], v52, v12, v[66:69]
	v_mfma_f32_16x16x4_f32 v[70:73], v64, v12, v[70:73]
	v_mfma_f32_16x16x4_f32 v[74:77], v80, v12, v[74:77]
	v_mfma_f32_16x16x4_f32 v[42:45], v45, v13, v[54:57]
	v_mfma_f32_16x16x4_f32 v[50:53], v53, v13, v[66:69]
	v_mfma_f32_16x16x4_f32 v[54:57], v65, v13, v[70:73]
	v_mfma_f32_16x16x4_f32 v[62:65], v81, v13, v[74:77]
	v_mfma_f32_16x16x4_f32 v[42:45], v26, v14, v[42:45]
	v_mfma_f32_16x16x4_f32 v[50:53], v38, v14, v[50:53]
	v_mfma_f32_16x16x4_f32 v[54:57], v46, v14, v[54:57]
	v_mfma_f32_16x16x4_f32 v[62:65], v58, v14, v[62:65]
	v_mfma_f32_16x16x4_f32 v[42:45], v27, v15, v[42:45]
	v_mfma_f32_16x16x4_f32 v[50:53], v39, v15, v[50:53]
	v_mfma_f32_16x16x4_f32 v[54:57], v47, v15, v[54:57]
	v_mfma_f32_16x16x4_f32 v[62:65], v59, v15, v[62:65]
	v_mfma_f32_16x16x4_f32 v[42:45], v28, v16, v[42:45]
	v_mfma_f32_16x16x4_f32 v[50:53], v40, v16, v[50:53]
	v_mfma_f32_16x16x4_f32 v[54:57], v48, v16, v[54:57]
	v_mfma_f32_16x16x4_f32 v[62:65], v60, v16, v[62:65]
	v_mfma_f32_16x16x4_f32 v[26:29], v29, v17, v[42:45]
	v_mfma_f32_16x16x4_f32 v[38:41], v41, v17, v[50:53]
	v_mfma_f32_16x16x4_f32 v[42:45], v49, v17, v[54:57]
	v_mfma_f32_16x16x4_f32 v[46:49], v61, v17, v[62:65]
	v_mfma_f32_16x16x4_f32 v[26:29], v4, v18, v[26:29]
	v_mfma_f32_16x16x4_f32 v[38:41], v22, v18, v[38:41]
	v_mfma_f32_16x16x4_f32 v[42:45], v30, v18, v[42:45]
	v_mfma_f32_16x16x4_f32 v[46:49], v34, v18, v[46:49]
	v_mfma_f32_16x16x4_f32 v[26:29], v5, v19, v[26:29]
	v_lshl_add_u64 v[4:5], v[228:229], 0, s[16:17]
	global_store_dwordx4 v[4:5], v[0:3], off sc1
	global_store_dwordx4 v[4:5], v[10:13], off offset:1024 sc1
	global_store_dwordx4 v[4:5], v[14:17], off offset:2048 sc1
	global_store_dwordx4 v[4:5], v[18:21], off offset:3072 sc1
	v_mfma_f32_16x16x4_f32 v[38:41], v23, v19, v[38:41]
	v_mfma_f32_16x16x4_f32 v[42:45], v31, v19, v[42:45]
	v_mfma_f32_16x16x4_f32 v[46:49], v35, v19, v[46:49]
	v_mfma_f32_16x16x4_f32 v[26:29], v6, v20, v[26:29]
	v_mfma_f32_16x16x4_f32 v[38:41], v24, v20, v[38:41]
	v_mfma_f32_16x16x4_f32 v[42:45], v32, v20, v[42:45]
	v_mfma_f32_16x16x4_f32 v[46:49], v36, v20, v[46:49]
	v_mfma_f32_16x16x4_f32 v[0:3], v7, v21, v[26:29]
	v_mfma_f32_16x16x4_f32 v[10:13], v25, v21, v[38:41]
	v_mfma_f32_16x16x4_f32 v[14:17], v33, v21, v[42:45]
	v_mfma_f32_16x16x4_f32 v[18:21], v37, v21, v[46:49]
	s_cbranch_scc1 .LBB0_1106
	v_mov_b64_e32 v[34:35], v[154:155]
	v_mov_b64_e32 v[58:59], v[158:159]
	v_mov_b64_e32 v[78:79], v[162:163]
	v_mov_b64_e32 v[86:87], v[166:167]
	v_mov_b64_e32 v[30:31], v[150:151]
	v_mov_b64_e32 v[46:47], v[138:139]
	v_mov_b64_e32 v[62:63], v[142:143]
	v_mov_b64_e32 v[82:83], v[146:147]
	v_mov_b64_e32 v[22:23], v[118:119]
	v_mov_b64_e32 v[38:39], v[122:123]
	v_mov_b64_e32 v[50:51], v[126:127]
	v_mov_b64_e32 v[66:67], v[130:131]
	v_mov_b64_e32 v[4:5], v[106:107]
	v_mov_b64_e32 v[26:27], v[94:95]
	v_mov_b64_e32 v[42:43], v[98:99]
	v_mov_b64_e32 v[54:55], v[102:103]
	v_mov_b64_e32 v[110:111], v[174:175]
	v_mov_b64_e32 v[90:91], v[170:171]
	v_mov_b64_e32 v[74:75], v[134:135]
	v_mov_b64_e32 v[70:71], v[114:115]
	s_mov_b32 s13, s23
	v_mov_b64_e32 v[36:37], v[156:157]
	v_mov_b64_e32 v[60:61], v[160:161]
	v_mov_b64_e32 v[80:81], v[164:165]
	v_mov_b64_e32 v[88:89], v[168:169]
	v_mov_b64_e32 v[32:33], v[152:153]
	v_mov_b64_e32 v[48:49], v[140:141]
	v_mov_b64_e32 v[64:65], v[144:145]
	v_mov_b64_e32 v[84:85], v[148:149]
	v_mov_b64_e32 v[24:25], v[120:121]
	v_mov_b64_e32 v[40:41], v[124:125]
	v_mov_b64_e32 v[52:53], v[128:129]
	v_mov_b64_e32 v[68:69], v[132:133]
	v_mov_b64_e32 v[6:7], v[108:109]
	v_mov_b64_e32 v[28:29], v[96:97]
	v_mov_b64_e32 v[44:45], v[100:101]
	v_mov_b64_e32 v[56:57], v[104:105]
	v_mov_b64_e32 v[112:113], v[176:177]
	v_mov_b64_e32 v[92:93], v[172:173]
	v_mov_b64_e32 v[76:77], v[136:137]
	v_mov_b64_e32 v[72:73], v[116:117]
	s_mov_b32 s21, s22
	s_add_i32 s22, s21, 1
	s_cmp_lt_u32 s22, s10
	s_mov_b64 s[16:17], -1
	s_cbranch_scc0 .LBB0_1101
	s_branch .LBB0_1102

.LBB0_1136:
	s_andn2_saveexec_b64 s[8:9], s[12:13]
	s_cbranch_execz .LBB0_1152
	s_add_i32 s101, s101, 1
	v_mov_b32_e32 v1, s50
	v_add_co_u32_e32 v2, vcc, 0x3000, v1
	v_mov_b32_e32 v1, s51
	s_nop 0
	s_waitcnt vmcnt(0)
	v_addc_co_u32_e32 v3, vcc, 0, v1, vcc
	flat_atomic_add v1, v[2:3], v228 offset:1024 sc0
	v_cvt_f32_u32_e32 v2, v0
	v_sub_u32_e32 v3, 0, v0
	s_add_u32 s12, s50, 0x3400
	s_addc_u32 s13, s51, 0
	v_rcp_iflag_f32_e32 v2, v2
	s_mov_b64 s[16:17], -1
	v_mul_f32_e32 v2, 0x4f7ffffe, v2
	v_cvt_u32_f32_e32 v2, v2
	v_mul_lo_u32 v3, v3, v2
	v_mul_hi_u32 v3, v2, v3
	v_add_u32_e32 v2, v2, v3
	s_waitcnt vmcnt(0) lgkmcnt(0)
	v_mul_hi_u32 v2, v1, v2
	v_mul_lo_u32 v3, v2, v0
	v_sub_u32_e32 v3, v1, v3
	v_cmp_ge_u32_e32 vcc, v3, v0
	v_add_u32_e32 v4, 1, v2
	s_nop 0
	v_cndmask_b32_e32 v2, v2, v4, vcc
	v_sub_u32_e32 v4, v3, v0
	v_cndmask_b32_e32 v3, v3, v4, vcc
	v_cmp_ge_u32_e32 vcc, v3, v0
	v_add_u32_e32 v3, 1, v2
	s_nop 0
	v_cndmask_b32_e32 v2, v2, v3, vcc
	v_add_u32_e32 v3, 1, v1
	v_mad_u64_u32 v[0:1], s[8:9], v0, v2, v[0:1]
	v_cmp_ne_u32_e32 vcc, v3, v0
	v_mov_b32_e32 v3, v0
	v_mov_b64_e32 v[0:1], s[12:13]
	s_and_saveexec_b64 s[14:15], vcc
	s_cbranch_execz .LBB0_1149
	v_mov_b64_e32 v[0:1], s[12:13]
	flat_load_dword v0, v[0:1] sc1
	s_mov_b64 s[20:21], 0
	s_waitcnt vmcnt(0) lgkmcnt(0)
	v_cmp_lt_u32_e32 vcc, v0, v3
	s_and_saveexec_b64 s[18:19], vcc
	s_cbranch_execz .LBB0_1148
	s_add_u32 s16, s50, 0x200
	s_addc_u32 s17, s51, 0
	s_mov_b32 s7, 1
	s_branch .LBB0_1141
